# v27 plus diff loop issues K fragment LDS reads before the ALiBi bias VALU block (bias temps renamed)
# baseline (speedup 1.0000x reference)
; template <int DQK, bool ALIBI>
; DI void attn_pass(const u16* __restrict__ Qp, int ldq, const u16* __restrict__ Kp, int ldk, const u16* __restrict__ VTp,
;                   int seq_start, int kt_lo, int kt_hi, int q0, float slope2, f32x16 (&O)[4], float& lsum, char* lds) {
;     ...
;     if (ALIBI) {
;       const float dq = qpos - (float)kb;
;       if (kb + 64 <= qw0 || kb > qw0 + 31) {
;         const float sl = (kb + 64 <= qw0) ? slope2 : -slope2;
;         const float T0 = -sl * dq, T1 = T0 + 32.f * sl;
; #pragma unroll
;         for (int i = 0; i < 16; ++i) {
;           S0[i] = fmaf(sl, (float)((i & 3) + 8 * (i >> 2)), T0);
;           S1[i] = fmaf(sl, (float)((i & 3) + 8 * (i >> 2)), T1);
;         }
;       } else {
; #pragma unroll
;         for (int i = 0; i < 16; ++i) {
;           S0[i] = -slope2 * fabsf(dq - (float)((i & 3) + 8 * (i >> 2)));
;           S1[i] = -slope2 * fabsf(dq - 32.f - (float)((i & 3) + 8 * (i >> 2)));
;         }
;       }
;     } else {
; #pragma unroll
;       for (int e = 0; e < 16; ++e) { S0[e] = 0.f; S1[e] = 0.f; }
;     }
;     bf16x8 k0[NKS], k1[NKS], vf[2][4];
; #pragma unroll
;     for (int ks = 0; ks < NKS; ++ks) {
;       k0[ks] = *(const bf16x8*)(Ks + r * KST + ks * 16 + h * 8);
;       k1[ks] = *(const bf16x8*)(Ks + (32 + r) * KST + ks * 16 + h * 8);
;     }
.LBB0_1149:
	s_and_b32 s46, s87, 1
	s_mul_i32 s46, s46, 0x6c00
	v_add_u32_e32 v205, s46, v156
	v_lshl_add_u32 v205, v153, 1, v205
	ds_read_b128 v[160:163], v205
	ds_read_b128 v[164:167], v205 offset:32
	ds_read_b128 v[176:179], v205 offset:64
	ds_read_b128 v[180:183], v205 offset:96
	ds_read_b128 v[168:171], v205 offset:4608
	ds_read_b128 v[172:175], v205 offset:4640
	ds_read_b128 v[184:187], v205 offset:4672
	ds_read_b128 v[194:197], v205 offset:4704
	v_cvt_f32_u32_e32 v66, s89
	s_add_i32 s88, s89, 64
	v_cmp_gt_i32_e64 s[44:45], s88, v129
	v_cmp_le_i32_e64 s[46:47], s89, v155
	v_cmp_le_i32_e32 vcc, s88, v129
	v_sub_f32_e32 v144, v154, v66
	s_and_b64 s[6:7], s[44:45], s[46:47]
	s_and_saveexec_b64 s[44:45], s[6:7]
	s_xor_b64 s[6:7], exec, s[44:45]
	s_cbranch_execz .LBB0_1151
	v_add_f32_e32 v68, s38, v144
	v_add_f32_e32 v69, s39, v144
	v_add_f32_e32 v84, s74, v144
	v_add_f32_e32 v85, s75, v144
	v_add_f32_e32 v67, -1.0, v144
	v_add_f32_e32 v66, 0xc2000000, v144
	v_add_f32_e32 v72, s18, v144
	v_add_f32_e32 v73, s19, v144
	v_add_f32_e32 v76, s4, v144
	v_add_f32_e32 v77, s5, v144
	v_add_f32_e32 v82, s24, v144
	v_add_f32_e32 v83, s25, v144
	v_add_f32_e32 v86, s22, v144
	v_add_f32_e32 v87, s23, v144
	v_and_b32_e32 v69, 0x7fffffff, v69
	v_and_b32_e32 v68, 0x7fffffff, v68
	v_and_b32_e32 v85, 0x7fffffff, v85
	v_and_b32_e32 v84, 0x7fffffff, v84
	v_mov_b32_e32 v131, v130
	v_add_f32_e32 v204, -1.0, v66
	v_add_f32_e32 v70, s38, v66
	v_add_f32_e32 v71, s39, v66
	v_add_f32_e32 v74, s18, v66
	v_add_f32_e32 v75, s19, v66
	v_add_f32_e32 v78, s4, v66
	v_add_f32_e32 v79, s5, v66
	v_add_f32_e32 v80, s34, v144
	v_add_f32_e32 v81, s35, v144
	v_add_f32_e32 v198, s34, v66
	v_add_f32_e32 v199, s35, v66
	v_add_f32_e32 v200, s24, v66
	v_add_f32_e32 v201, s25, v66
	v_add_f32_e32 v202, s74, v66
	v_add_f32_e32 v203, s75, v66
	v_and_b32_e32 v73, 0x7fffffff, v73
	v_and_b32_e32 v72, 0x7fffffff, v72
	v_and_b32_e32 v77, 0x7fffffff, v77
	v_and_b32_e32 v76, 0x7fffffff, v76
	v_and_b32_e32 v83, 0x7fffffff, v83
	v_and_b32_e32 v82, 0x7fffffff, v82
	v_and_b32_e32 v87, 0x7fffffff, v87
	v_and_b32_e32 v86, 0x7fffffff, v86
	v_and_b32_e32 v144, 0x7fffffff, v144
	v_and_b32_e32 v145, 0x7fffffff, v67
	v_mul_f32_e32 v94, v84, v130
	v_mul_f32_e32 v95, v85, v131
	v_mul_f32_e32 v84, v68, v130
	v_mul_f32_e32 v85, v69, v131
	v_add_f32_e32 v68, s22, v66
	v_add_f32_e32 v69, s23, v66
	v_and_b32_e32 v81, 0x7fffffff, v81
	v_and_b32_e32 v80, 0x7fffffff, v80
	v_mul_f32_e32 v96, v86, v130
	v_mul_f32_e32 v97, v87, v131
	v_mul_f32_e32 v92, v82, v130
	v_mul_f32_e32 v93, v83, v131
	v_mul_f32_e32 v88, v76, v130
	v_mul_f32_e32 v89, v77, v131
	v_mul_f32_e32 v86, v72, v130
	v_mul_f32_e32 v87, v73, v131
	v_mul_f32_e32 v82, v144, v134
	v_mul_f32_e32 v83, v145, v135
	v_and_b32_e32 v145, 0x7fffffff, v71
	v_and_b32_e32 v144, 0x7fffffff, v70
	v_and_b32_e32 v71, 0x7fffffff, v75
	v_and_b32_e32 v70, 0x7fffffff, v74
	v_and_b32_e32 v73, 0x7fffffff, v79
	v_and_b32_e32 v72, 0x7fffffff, v78
	v_and_b32_e32 v75, 0x7fffffff, v199
	v_and_b32_e32 v74, 0x7fffffff, v198
	v_and_b32_e32 v77, 0x7fffffff, v201
	v_and_b32_e32 v76, 0x7fffffff, v200
	v_and_b32_e32 v79, 0x7fffffff, v203
	v_and_b32_e32 v78, 0x7fffffff, v202
	v_and_b32_e32 v69, 0x7fffffff, v69
	v_and_b32_e32 v68, 0x7fffffff, v68
	v_and_b32_e32 v66, 0x7fffffff, v66
	v_and_b32_e32 v67, 0x7fffffff, v204
	v_mul_f32_e32 v90, v80, v130
	v_mul_f32_e32 v91, v81, v131
	v_mul_f32_e32 v80, v68, v130
	v_mul_f32_e32 v81, v69, v131
	v_mul_f32_e32 v78, v78, v130
	v_mul_f32_e32 v79, v79, v131
	v_mul_f32_e32 v76, v76, v130
	v_mul_f32_e32 v77, v77, v131
	v_mul_f32_e32 v74, v74, v130
	v_mul_f32_e32 v75, v75, v131
	v_mul_f32_e32 v72, v72, v130
	v_mul_f32_e32 v73, v73, v131
	v_mul_f32_e32 v70, v70, v130
	v_mul_f32_e32 v71, v71, v131
	v_mul_f32_e32 v68, v144, v130
	v_mul_f32_e32 v69, v145, v131
	v_mul_f32_e32 v66, v66, v134
	v_mul_f32_e32 v67, v67, v135
.LBB0_1151:
	s_andn2_saveexec_b64 s[6:7], s[6:7]
	s_cbranch_execz .LBB0_1153
	v_cndmask_b32_e64 v145, -v149, v149, vcc
	v_xor_b32_e32 v192, 0x80000000, v145
	v_mul_f32_e32 v80, v144, v192
	v_mul_f32_e32 v81, v145, v193
	v_fma_f32 v198, v144, v192, v81
	v_fma_f32 v199, v145, v193, v80
	v_mov_b32_e32 v144, v145
	v_fma_f32 v82, 0, v145, v80
	v_fma_f32 v66, 0, v145, v198
	v_add_f32_e32 v83, v145, v80
	v_add_f32_e32 v67, v145, v198
	v_fma_f32 v84, v144, s20, v80
	v_fma_f32 v85, v144, s21, v80
	v_fma_f32 v68, v144, s20, v198
	v_fma_f32 v69, v144, s21, v198
	v_fma_f32 v86, v144, s8, v80
	v_fma_f32 v87, v144, s9, v80
	v_fma_f32 v70, v144, s8, v198
	v_fma_f32 v71, v144, s9, v198
	v_fma_f32 v88, v144, s26, v80
	v_fma_f32 v89, v144, s27, v80
	v_fma_f32 v72, v144, s26, v198
	v_fma_f32 v73, v144, s27, v198
	v_fma_f32 v90, v144, s28, v80
	v_fma_f32 v91, v144, s29, v80
	v_fma_f32 v74, v144, s28, v198
	v_fma_f32 v75, v144, s29, v198
	v_fma_f32 v92, v144, s30, v80
	v_fma_f32 v93, v144, s31, v80
	v_fma_f32 v76, v144, s30, v198
	v_fma_f32 v77, v144, s31, v198
	v_fma_f32 v94, v144, s36, v80
	v_fma_f32 v95, v144, s37, v80
	v_fma_f32 v78, v144, s36, v198
	v_fma_f32 v79, v144, s37, v198
	v_fma_f32 v96, v144, s78, v80
	v_fma_f32 v97, v144, s79, v80
	v_fma_f32 v80, v144, s78, v198
	v_fma_f32 v81, v144, s79, v198
; #define MFMA(a, b, c) __builtin_amdgcn_mfma_f32_32x32x16_bf16((a), (b), (c), 0, 0, 0)
; template <int DQK, bool ALIBI>
; DI void attn_pass(const u16* __restrict__ Qp, int ldq, const u16* __restrict__ Kp, int ldk, const u16* __restrict__ VTp,
;                   int seq_start, int kt_lo, int kt_hi, int q0, float slope2, f32x16 (&O)[4], float& lsum, char* lds) {
;     ...
;     __builtin_amdgcn_sched_barrier(0);
; #pragma unroll
;     for (int ks = 0; ks < NKS; ++ks) {
;       S0 = MFMA(k0[ks], qf[ks], S0);
;       S1 = MFMA(k1[ks], qf[ks], S1);
;     }
;     if (kt + 1 < kt_hi) ATT_LSTORE(cur ^ 1);
;     if (kt + 2 < kt_hi) ATT_GLOAD(kt + 2);
; #pragma unroll
;     for (int s = 0; s < 2; ++s)
; #pragma unroll
;       for (int db = 0; db < 4; ++db) vf[s][db] = *(const bf16x8*)(Vs + (db * 32 + r) * 72 + s * 16 + h * 8);
;     __builtin_amdgcn_sched_barrier(0);
;     bf16x8 pf[2];
;     ...
;     ATT_SOFTMAX(S0);
;     __builtin_amdgcn_sched_barrier(0);
; #pragma unroll
;     for (int s = 0; s < 2; ++s)
; #pragma unroll
;       for (int db = 0; db < 4; ++db) O[db] = MFMA(vf[s][db], pf[s], O[db]);
;     bf16x8 vg[2][4];
; #pragma unroll
;     for (int s = 0; s < 2; ++s)
; #pragma unroll
;       for (int db = 0; db < 4; ++db) vg[s][db] = *(const bf16x8*)(Vs + (db * 32 + r) * 72 + 32 + s * 16 + h * 8);
;     bf16x8 pg[2];
;     {
;       float pv[16];
; #pragma unroll
;       for (int i = 0; i < 16; ++i) pv[i] = __builtin_amdgcn_exp2f(S1[i]);
; #pragma unroll
;       for (int i = 0; i < 8; ++i) l2 += f32x2{pv[2 * i], pv[2 * i + 1]};
; #pragma unroll
;       for (int s = 0; s < 2; ++s) {
;         u32 a0 = pack2(pv[8 * s], pv[8 * s + 1]), a1 = pack2(pv[8 * s + 2], pv[8 * s + 3]);
;         u32 a2 = pack2(pv[8 * s + 4], pv[8 * s + 5]), a3 = pack2(pv[8 * s + 6], pv[8 * s + 7]);
;         u32x4 pk = {a0, a1, a2, a3};
;         pg[s] = __builtin_bit_cast(bf16x8, pk);
;       }
;     }
.LBB0_1153:
	s_or_b64 exec, exec, s[6:7]
	s_and_b32 s6, s87, 1
	s_mul_i32 s44, s6, 0x6c00
	v_add_u32_e32 v131, s44, v156
	s_waitcnt lgkmcnt(7)
	v_mfma_f32_32x32x16_bf16 v[82:97], v[160:163], v[98:101], v[82:97]
	s_waitcnt lgkmcnt(6)
	v_mfma_f32_32x32x16_bf16 v[82:97], v[164:167], v[102:105], v[82:97]
	s_waitcnt lgkmcnt(5)
	v_mfma_f32_32x32x16_bf16 v[82:97], v[176:179], v[106:109], v[82:97]
	s_waitcnt lgkmcnt(4)
	v_mfma_f32_32x32x16_bf16 v[82:97], v[180:183], v[110:113], v[82:97]
	s_waitcnt lgkmcnt(3)
	v_mfma_f32_32x32x16_bf16 v[66:81], v[168:171], v[98:101], v[66:81]
	s_waitcnt lgkmcnt(2)
	v_mfma_f32_32x32x16_bf16 v[66:81], v[172:175], v[102:105], v[66:81]
	v_add3_u32 v144, s44, v0, v156
	ds_read_b128 v[160:163], v144 offset:9216
	ds_read_b128 v[164:167], v144 offset:9248
	ds_read_b128 v[168:171], v144 offset:13824
	ds_read_b128 v[172:175], v144 offset:13856
	ds_read_b128 v[176:179], v144 offset:18432
	ds_read_b128 v[180:183], v144 offset:18464
	s_waitcnt lgkmcnt(7)
	v_mfma_f32_32x32x16_bf16 v[66:81], v[184:187], v[106:109], v[66:81]
	v_exp_f32_e32 v82, v82
	v_exp_f32_e32 v83, v83
	v_exp_f32_e32 v84, v84
	v_exp_f32_e32 v85, v85
	s_waitcnt lgkmcnt(6)
	v_mfma_f32_32x32x16_bf16 v[66:81], v[194:197], v[110:113], v[66:81]
	ds_read_b128 v[184:187], v144 offset:23040
	ds_read_b128 v[194:197], v144 offset:23072
	v_exp_f32_e32 v86, v86
	v_exp_f32_e32 v87, v87
	v_exp_f32_e32 v88, v88
	v_exp_f32_e32 v89, v89
	v_exp_f32_e32 v90, v90
	v_exp_f32_e32 v91, v91
	v_exp_f32_e32 v92, v92
	v_exp_f32_e32 v93, v93
	v_exp_f32_e32 v94, v94
	v_exp_f32_e32 v95, v95
	v_exp_f32_e32 v96, v96
	v_exp_f32_e32 v97, v97
	v_add_f32_e32 v142, v142, v82
	v_add_f32_e32 v143, v143, v83
	v_add_f32_e32 v142, v84, v142
	v_add_f32_e32 v143, v85, v143
	v_add_f32_e32 v142, v86, v142
	v_add_f32_e32 v143, v87, v143
	v_add_f32_e32 v142, v88, v142
	v_add_f32_e32 v143, v89, v143
	v_add_f32_e32 v142, v90, v142
	v_add_f32_e32 v143, v91, v143
	v_add_f32_e32 v142, v92, v142
	v_add_f32_e32 v143, v93, v143
	v_add_f32_e32 v142, v94, v142
	v_add_f32_e32 v143, v95, v143
	v_add_f32_e32 v142, v96, v142
	v_add_f32_e32 v143, v97, v143
	v_cvt_pk_bf16_f32 v82, v82, v83
	v_cvt_pk_bf16_f32 v83, v84, v85
	v_cvt_pk_bf16_f32 v84, v86, v87
	v_cvt_pk_bf16_f32 v85, v88, v89
	v_cvt_pk_bf16_f32 v86, v90, v91
	v_cvt_pk_bf16_f32 v87, v92, v93
	v_cvt_pk_bf16_f32 v88, v94, v95
	v_cvt_pk_bf16_f32 v89, v96, v97
	s_waitcnt lgkmcnt(7)
	v_mfma_f32_32x32x16_bf16 v[50:65], v[160:163], v[82:85], v[50:65]
	v_exp_f32_e32 v66, v66
	v_exp_f32_e32 v67, v67
	v_exp_f32_e32 v68, v68
	v_exp_f32_e32 v69, v69
	s_waitcnt lgkmcnt(5)
	v_mfma_f32_32x32x16_bf16 v[34:49], v[168:171], v[82:85], v[34:49]
	v_exp_f32_e32 v70, v70
	v_exp_f32_e32 v71, v71
	v_exp_f32_e32 v72, v72
	v_exp_f32_e32 v73, v73
	s_waitcnt lgkmcnt(3)
	v_mfma_f32_32x32x16_bf16 v[18:33], v[176:179], v[82:85], v[18:33]
	v_exp_f32_e32 v74, v74
	v_exp_f32_e32 v75, v75
	v_exp_f32_e32 v76, v76
	v_exp_f32_e32 v77, v77
	v_mfma_f32_32x32x16_bf16 v[50:65], v[164:167], v[86:89], v[50:65]
	ds_read_b128 v[160:163], v144 offset:9312
	ds_read_b128 v[168:171], v144 offset:18528
	v_exp_f32_e32 v78, v78
	v_exp_f32_e32 v79, v79
	v_exp_f32_e32 v80, v80
	v_exp_f32_e32 v81, v81
	v_mfma_f32_32x32x16_bf16 v[34:49], v[172:175], v[86:89], v[34:49]
	ds_read_b128 v[164:167], v144 offset:13920
	ds_read_b128 v[90:93], v144 offset:18496
	ds_read_b128 v[94:97], v144 offset:23104
	v_add_f32_e32 v142, v66, v142
	v_add_f32_e32 v143, v67, v143
	v_add_f32_e32 v142, v68, v142
	v_add_f32_e32 v143, v69, v143
	s_waitcnt lgkmcnt(7)
	v_mfma_f32_32x32x16_bf16 v[18:33], v[180:183], v[86:89], v[18:33]
	ds_read_b128 v[198:201], v144 offset:9280
	v_add_f32_e32 v142, v70, v142
	v_add_f32_e32 v143, v71, v143
	v_add_f32_e32 v142, v72, v142
	v_add_f32_e32 v143, v73, v143
	s_waitcnt lgkmcnt(7)
	v_mfma_f32_32x32x16_bf16 v[2:17], v[184:187], v[82:85], v[2:17]
	v_add_f32_e32 v142, v74, v142
	v_add_f32_e32 v143, v75, v143
	v_add_f32_e32 v142, v76, v142
	v_add_f32_e32 v143, v77, v143
	s_waitcnt lgkmcnt(6)
	v_mfma_f32_32x32x16_bf16 v[2:17], v[194:197], v[86:89], v[2:17]
	ds_read_b128 v[86:89], v144 offset:13888
	ds_read_b128 v[82:85], v144 offset:23136
	v_add_f32_e32 v142, v78, v142
	v_add_f32_e32 v143, v79, v143
	v_add_f32_e32 v142, v80, v142
	v_add_f32_e32 v143, v81, v143
	v_cvt_pk_bf16_f32 v66, v66, v67
	v_cvt_pk_bf16_f32 v67, v68, v69
	v_cvt_pk_bf16_f32 v68, v70, v71
	v_cvt_pk_bf16_f32 v69, v72, v73
	v_cvt_pk_bf16_f32 v70, v74, v75
	v_cvt_pk_bf16_f32 v71, v76, v77
	v_cvt_pk_bf16_f32 v72, v78, v79
	v_cvt_pk_bf16_f32 v73, v80, v81
	s_waitcnt lgkmcnt(2)
	v_mfma_f32_32x32x16_bf16 v[50:65], v[198:201], v[66:69], v[50:65]
	s_waitcnt lgkmcnt(1)
	v_mfma_f32_32x32x16_bf16 v[34:49], v[86:89], v[66:69], v[34:49]
	s_waitcnt lgkmcnt(0)
	s_add_i32 s45, s73, s87
	s_add_i32 s7, s45, 1
	s_cmp_ge_i32 s7, s77
	s_cbranch_scc1 .Lmy_dif_w2
	s_and_b32 s6, s87, 1
	s_xor_b32 s46, s6, 1
	s_mulk_i32 s46, 0x6c00
	s_and_saveexec_b64 s[6:7], s[42:43]
	s_cbranch_execz .Lmy_dif_w1
	v_add3_u32 v144, s46, v157, v158
	s_waitcnt vmcnt(2)
	ds_write_b128 v144, v[114:117]
